# attention unit prologue: q-finalize gain vector loads software-pipelined three chunks ahead instead of load-wait per chunk
# speedup vs baseline: 1.0033x; 1.0033x over previous
.LBB0_562:
	v_mov_b32_e32 v41, v181
	s_add_i32 s7, 0, 0x14000
	v_ashrrev_i32_e32 v0, 6, v41
	v_and_b32_e32 v1, 0x3fffffc0, v41
	s_and_b32 s5, s5, 7
	v_and_b32_e32 v168, 31, v41
	v_lshl_add_u32 v169, v1, 2, s7
	s_movk_i32 s7, 0x1800
	v_lshl_add_u32 v170, v0, 5, s6
	v_mul_lo_u32 v37, v0, s7
	v_add_u32_e32 v36, v170, v168
	v_mov_b64_e32 v[0:1], s[60:61]
	s_mul_i32 s11, s5, 0xc0
	v_bfe_u32 v159, v41, 5, 1
	v_mad_i64_i32 v[0:1], s[6:7], v36, s87, v[0:1]
	s_lshl_b32 s44, s11, 1
	v_lshl_add_u64 v[0:1], v[0:1], 0, s[44:45]
	v_lshlrev_b32_e32 v176, 4, v159
	v_lshl_add_u64 v[4:5], v[0:1], 0, v[176:177]
	global_load_dwordx4 v[42:45], v[4:5], off
	global_load_dwordx4 v[46:49], v[4:5], off offset:32
	global_load_dwordx4 v[50:53], v[4:5], off offset:64
	global_load_dwordx4 v[32:35], v[4:5], off offset:96
	global_load_dwordx4 v[28:31], v[4:5], off offset:128
	global_load_dwordx4 v[24:27], v[4:5], off offset:160
	global_load_dwordx4 v[20:23], v[4:5], off offset:192
	global_load_dwordx4 v[16:19], v[4:5], off offset:224
	global_load_dwordx4 v[8:11], v[4:5], off offset:256
	global_load_dwordx4 v[12:15], v[4:5], off offset:288
	global_load_dwordx4 v[0:3], v[4:5], off offset:320
	s_nop 0
	global_load_dwordx4 v[4:7], v[4:5], off offset:352
	v_and_b32_e32 v66, 63, v41
	s_add_i32 s6, 0, 0x14800
	v_lshlrev_b32_e32 v67, 4, v66
	v_add_u32_e32 v37, s6, v37
	v_add_u32_e32 v171, v37, v67
	s_mov_b64 s[6:7], 0x40040
	v_ashrrev_i32_e32 v148, 4, v41
	s_cmp_lg_u32 0, -1
	s_cselect_b32 s16, 0, 0
	v_ashrrev_i32_e32 v149, 31, v148
	v_lshl_add_u64 v[156:157], v[148:149], 0, 32
	s_mov_b32 s46, s45
	s_mov_b32 s47, s45
	s_mov_b32 s48, s45
	s_mov_b32 s49, s45
	s_mov_b32 s50, s45
	s_mov_b32 s51, s45
	s_mov_b32 s52, s45
	s_mov_b32 s53, s45
	s_mov_b32 s54, s45
	s_mov_b32 s55, s45
	s_mov_b32 s56, s45
	s_mov_b32 s57, s45
	s_mov_b32 s58, s45
	s_mov_b32 s59, s45
	s_mov_b32 s13, 2
	v_lshl_add_u32 v173, v168, 2, v169
	v_mov_b32_e32 v188, 0
	s_waitcnt vmcnt(0)
	v_and_b32_e32 v68, 0xffff0000, v42
	v_and_b32_e32 v70, 0xffff0000, v43
	v_lshlrev_b32_e32 v69, 16, v42
	v_mul_f32_e32 v38, v68, v68
	v_lshlrev_b32_e32 v71, 16, v43
	v_mul_f32_e32 v39, v70, v70
	v_fmac_f32_e32 v38, v69, v69
	v_fmac_f32_e32 v39, v71, v71
	v_and_b32_e32 v72, 0xffff0000, v44
	v_add_f32_e32 v38, v38, v39
	v_lshlrev_b32_e32 v73, 16, v44
	v_mul_f32_e32 v39, v72, v72
	v_fmac_f32_e32 v39, v73, v73
	v_and_b32_e32 v76, 0xffff0000, v45
	v_add_f32_e32 v38, v39, v38
	v_lshlrev_b32_e32 v77, 16, v45
	v_mul_f32_e32 v39, v76, v76
	v_fmac_f32_e32 v39, v77, v77
	v_and_b32_e32 v74, 0xffff0000, v46
	v_add_f32_e32 v38, v39, v38
	v_lshlrev_b32_e32 v75, 16, v46
	v_mul_f32_e32 v39, v74, v74
	v_fmac_f32_e32 v39, v75, v75
	v_and_b32_e32 v78, 0xffff0000, v47
	v_add_f32_e32 v38, v39, v38
	v_lshlrev_b32_e32 v79, 16, v47
	v_mul_f32_e32 v39, v78, v78
	v_fmac_f32_e32 v39, v79, v79
	v_and_b32_e32 v80, 0xffff0000, v48
	v_add_f32_e32 v38, v39, v38
	v_lshlrev_b32_e32 v82, 16, v48
	v_mul_f32_e32 v39, v80, v80
	v_fmac_f32_e32 v39, v82, v82
	v_and_b32_e32 v85, 0xffff0000, v49
	v_add_f32_e32 v38, v39, v38
	v_lshlrev_b32_e32 v86, 16, v49
	v_mul_f32_e32 v39, v85, v85
	v_fmac_f32_e32 v39, v86, v86
	v_and_b32_e32 v83, 0xffff0000, v50
	v_add_f32_e32 v38, v39, v38
	v_lshlrev_b32_e32 v84, 16, v50
	v_mul_f32_e32 v39, v83, v83
	v_fmac_f32_e32 v39, v84, v84
	v_and_b32_e32 v87, 0xffff0000, v51
	v_add_f32_e32 v38, v39, v38
	v_lshlrev_b32_e32 v88, 16, v51
	v_mul_f32_e32 v39, v87, v87
	v_fmac_f32_e32 v39, v88, v88
	v_and_b32_e32 v93, 0xffff0000, v52
	v_add_f32_e32 v38, v39, v38
	v_lshlrev_b32_e32 v95, 16, v52
	v_mul_f32_e32 v39, v93, v93
	v_fmac_f32_e32 v39, v95, v95
	v_and_b32_e32 v104, 0xffff0000, v53
	v_add_f32_e32 v38, v39, v38
	v_lshlrev_b32_e32 v105, 16, v53
	v_mul_f32_e32 v39, v104, v104
	v_and_b32_e32 v91, 0xffff0000, v32
	v_fmac_f32_e32 v39, v105, v105
	v_lshlrev_b32_e32 v108, 16, v32
	v_mul_f32_e32 v32, v91, v91
	v_and_b32_e32 v89, 0xffff0000, v33
	v_add_f32_e32 v38, v39, v38
	v_fmac_f32_e32 v32, v108, v108
	v_lshlrev_b32_e32 v94, 16, v33
	v_mul_f32_e32 v33, v89, v89
	v_add_f32_e32 v32, v32, v38
	v_fmac_f32_e32 v33, v94, v94
	v_and_b32_e32 v110, 0xffff0000, v34
	v_add_f32_e32 v32, v33, v32
	v_lshlrev_b32_e32 v112, 16, v34
	v_mul_f32_e32 v33, v110, v110
	v_fmac_f32_e32 v33, v112, v112
	v_and_b32_e32 v109, 0xffff0000, v35
	v_add_f32_e32 v32, v33, v32
	v_lshlrev_b32_e32 v111, 16, v35
	v_mul_f32_e32 v33, v109, v109
	v_and_b32_e32 v114, 0xffff0000, v28
	v_fmac_f32_e32 v33, v111, v111
	v_lshlrev_b32_e32 v113, 16, v28
	v_mul_f32_e32 v28, v114, v114
	v_and_b32_e32 v130, 0xffff0000, v29
	v_add_f32_e32 v32, v33, v32
	v_fmac_f32_e32 v28, v113, v113
	v_lshlrev_b32_e32 v115, 16, v29
	v_mul_f32_e32 v29, v130, v130
	v_add_f32_e32 v28, v28, v32
	v_fmac_f32_e32 v29, v115, v115
	v_and_b32_e32 v132, 0xffff0000, v30
	v_add_f32_e32 v28, v29, v28
	v_lshlrev_b32_e32 v131, 16, v30
	v_mul_f32_e32 v29, v132, v132
	v_fmac_f32_e32 v29, v131, v131
	v_and_b32_e32 v134, 0xffff0000, v31
	v_add_f32_e32 v28, v29, v28
	v_lshlrev_b32_e32 v133, 16, v31
	v_mul_f32_e32 v29, v134, v134
	v_and_b32_e32 v126, 0xffff0000, v24
	v_fmac_f32_e32 v29, v133, v133
	v_lshlrev_b32_e32 v128, 16, v24
	v_mul_f32_e32 v24, v126, v126
	v_and_b32_e32 v116, 0xffff0000, v25
	v_add_f32_e32 v28, v29, v28
	v_fmac_f32_e32 v24, v128, v128
	v_lshlrev_b32_e32 v118, 16, v25
	v_mul_f32_e32 v25, v116, v116
	v_add_f32_e32 v24, v24, v28
	v_fmac_f32_e32 v25, v118, v118
	v_and_b32_e32 v127, 0xffff0000, v26
	v_add_f32_e32 v24, v25, v24
	v_lshlrev_b32_e32 v129, 16, v26
	v_mul_f32_e32 v25, v127, v127
	v_fmac_f32_e32 v25, v129, v129
	v_and_b32_e32 v117, 0xffff0000, v27
	v_add_f32_e32 v24, v25, v24
	v_lshlrev_b32_e32 v119, 16, v27
	v_mul_f32_e32 v25, v117, v117
	v_and_b32_e32 v122, 0xffff0000, v20
	v_fmac_f32_e32 v25, v119, v119
	v_lshlrev_b32_e32 v124, 16, v20
	v_mul_f32_e32 v20, v122, v122
	v_and_b32_e32 v90, 0xffff0000, v21
	v_add_f32_e32 v24, v25, v24
	v_fmac_f32_e32 v20, v124, v124
	v_lshlrev_b32_e32 v120, 16, v21
	v_mul_f32_e32 v21, v90, v90
	v_add_f32_e32 v20, v20, v24
	v_fmac_f32_e32 v21, v120, v120
	v_and_b32_e32 v123, 0xffff0000, v22
	v_add_f32_e32 v20, v21, v20
	v_lshlrev_b32_e32 v125, 16, v22
	v_mul_f32_e32 v21, v123, v123
	v_fmac_f32_e32 v21, v125, v125
	v_and_b32_e32 v92, 0xffff0000, v23
	v_add_f32_e32 v20, v21, v20
	v_lshlrev_b32_e32 v121, 16, v23
	v_mul_f32_e32 v21, v92, v92
	v_fmac_f32_e32 v21, v121, v121
	v_add_f32_e32 v21, v21, v20
	v_and_b32_e32 v20, 0xffff0000, v16
	v_lshlrev_b32_e32 v22, 16, v16
	v_mul_f32_e32 v16, v20, v20
	v_fmac_f32_e32 v16, v22, v22
	v_add_f32_e32 v23, v16, v21
	v_and_b32_e32 v16, 0xffff0000, v17
	v_lshlrev_b32_e32 v21, 16, v17
	v_mul_f32_e32 v17, v16, v16
	v_fmac_f32_e32 v17, v21, v21
	v_lshlrev_b32_e32 v81, 16, v18
	v_and_b32_e32 v18, 0xffff0000, v18
	v_add_f32_e32 v17, v17, v23
	v_mul_f32_e32 v23, v18, v18
	v_fmac_f32_e32 v23, v81, v81
	v_add_f32_e32 v24, v23, v17
	v_and_b32_e32 v17, 0xffff0000, v19
	v_lshlrev_b32_e32 v23, 16, v19
	v_mul_f32_e32 v19, v17, v17
	v_fmac_f32_e32 v19, v23, v23
	v_add_f32_e32 v19, v19, v24
	v_and_b32_e32 v24, 32, v41
	global_load_dwordx4 v[96:99], v24, s[0:1] offset:16
	global_load_dwordx4 v[100:103], v24, s[0:1]
	global_load_dwordx4 v[240:243], v24, s[0:1] offset:80
	global_load_dwordx4 v[244:247], v24, s[0:1] offset:64
	global_load_dwordx4 v[248:251], v24, s[0:1] offset:144
	global_load_dwordx4 v[220:223], v24, s[0:1] offset:128
	global_load_dwordx4 v[232:235], v24, s[0:1] offset:208
	global_load_dwordx4 v[236:239], v24, s[0:1] offset:192
	v_and_b32_e32 v63, 0xffff0000, v12
	v_and_b32_e32 v62, 0xffff0000, v8
	v_mov_b32_e32 v25, v177
	v_lshlrev_b32_e32 v60, 16, v9
	v_and_b32_e32 v59, 0xffff0000, v13
	v_and_b32_e32 v58, 0xffff0000, v9
	v_lshlrev_b32_e32 v65, 16, v12
	v_lshlrev_b32_e32 v64, 16, v8
	v_pk_mul_f32 v[8:9], v[62:63], v[62:63]
	v_lshl_add_u64 v[26:27], s[40:41], 0, v[24:25]
	v_lshlrev_b32_e32 v25, 7, v36
	v_lshlrev_b32_e32 v39, 16, v15
	v_and_b32_e32 v37, 0xffff0000, v15
	v_lshlrev_b32_e32 v51, 16, v14
	v_and_b32_e32 v49, 0xffff0000, v14
	v_and_b32_e32 v48, 0xffff0000, v10
	v_lshlrev_b32_e32 v61, 16, v13
	v_pk_mul_f32 v[14:15], v[58:59], v[58:59]
	v_pk_fma_f32 v[8:9], v[64:65], v[64:65], v[8:9]
	v_and_b32_e32 v28, 0x3ff80, v25
	v_mov_b32_e32 v29, v177
	v_lshlrev_b32_e32 v38, 16, v11
	v_and_b32_e32 v36, 0xffff0000, v11
	v_lshlrev_b32_e32 v50, 16, v10
	v_pk_mul_f32 v[10:11], v[48:49], v[48:49]
	v_pk_fma_f32 v[14:15], v[60:61], v[60:61], v[14:15]
	v_add_f32_e32 v8, v8, v19
	v_lshl_add_u64 v[28:29], v[26:27], 0, v[28:29]
	v_pk_mul_f32 v[26:27], v[36:37], v[36:37]
	v_pk_fma_f32 v[10:11], v[50:51], v[50:51], v[10:11]
	v_add_f32_e32 v8, v14, v8
	v_pk_fma_f32 v[26:27], v[38:39], v[38:39], v[26:27]
	v_add_f32_e32 v8, v10, v8
	v_add_f32_e32 v8, v26, v8
	v_add_f32_e32 v8, v9, v8
	v_add_f32_e32 v8, v15, v8
	v_add_f32_e32 v8, v11, v8
	v_and_b32_e32 v26, 0xffff0000, v3
	v_and_b32_e32 v32, 0xffff0000, v2
	v_add_f32_e32 v10, v27, v8
	v_lshlrev_b32_e32 v31, 16, v7
	v_lshlrev_b32_e32 v30, 16, v3
	v_and_b32_e32 v27, 0xffff0000, v7
	v_lshlrev_b32_e32 v35, 16, v6
	v_lshlrev_b32_e32 v34, 16, v2
	v_and_b32_e32 v33, 0xffff0000, v6
	v_mov_b32_e32 v6, v26
	v_mov_b32_e32 v7, v32
	v_mov_b32_e32 v2, v30
	v_mov_b32_e32 v3, v34
	v_pk_mul_f32 v[6:7], v[6:7], v[6:7]
	v_mov_b32_e32 v8, v27
	v_mov_b32_e32 v9, v33
	v_pk_fma_f32 v[2:3], v[2:3], v[2:3], v[6:7]
	v_mov_b32_e32 v6, v31
	v_mov_b32_e32 v7, v35
	v_pk_mul_f32 v[8:9], v[8:9], v[8:9]
	v_and_b32_e32 v43, 0xffff0000, v5
	v_lshlrev_b32_e32 v56, 16, v0
	v_and_b32_e32 v53, 0xffff0000, v4
	v_pk_fma_f32 v[6:7], v[6:7], v[6:7], v[8:9]
	v_lshlrev_b32_e32 v47, 16, v5
	v_lshlrev_b32_e32 v46, 16, v1
	v_lshlrev_b32_e32 v57, 16, v4
	v_and_b32_e32 v52, 0xffff0000, v0
	v_mul_f32_e32 v9, v56, v56
	v_mov_b32_e32 v4, v43
	v_mov_b32_e32 v5, v53
	v_and_b32_e32 v42, 0xffff0000, v1
	v_mul_f32_e32 v8, v46, v46
	v_fmac_f32_e32 v9, v52, v52
	v_mov_b32_e32 v0, v47
	v_mov_b32_e32 v1, v57
	v_pk_mul_f32 v[4:5], v[4:5], v[4:5]
	v_fmac_f32_e32 v8, v42, v42
	v_pk_fma_f32 v[0:1], v[0:1], v[0:1], v[4:5]
	v_add_f32_e32 v4, v9, v10
	v_add_f32_e32 v4, v8, v4
	v_add_f32_e32 v3, v3, v4
	v_add_f32_e32 v2, v2, v3
	v_add_f32_e32 v1, v1, v2
	v_add_f32_e32 v0, v0, v1
	v_add_f32_e32 v0, v7, v0
	v_add_f32_e32 v0, v6, v0
	v_mov_b32_e32 v1, v0
	s_nop 1
	v_permlane32_swap_b32_e32 v0, v1
	v_add_f32_e32 v0, v0, v1
	v_fmamk_f32 v0, v0, 0x3baaaaab, v216
	v_cmp_gt_f32_e32 vcc, s85, v0
	v_mul_f32_e32 v1, 0x4b800000, v0
	v_lshl_add_u64 v[54:55], v[28:29], 0, s[30:31]
	v_cndmask_b32_e32 v0, v0, v1, vcc
	v_rsq_f32_e32 v0, v0
	v_lshl_add_u64 v[44:45], v[28:29], 0, s[6:7]
	v_mul_f32_e32 v1, 0x45800000, v0
	v_cndmask_b32_e32 v0, v0, v1, vcc
	v_mul_f32_e32 v40, 0x3dd53b94, v0
	v_mul_f32_e32 v0, v40, v69
	v_mul_f32_e32 v1, v40, v73
	v_mul_f32_e32 v2, v40, v68
	v_mul_f32_e32 v3, v40, v72
	v_mul_f32_e32 v4, v40, v71
	v_mul_f32_e32 v5, v40, v77
	v_mul_f32_e32 v6, v40, v70
	v_mul_f32_e32 v7, v40, v76
	s_waitcnt vmcnt(0)
	v_mul_f32_e32 v0, v100, v0
	v_mul_f32_e32 v1, v96, v1
	v_mul_f32_e32 v2, v101, v2
	v_mul_f32_e32 v3, v97, v3
	v_mul_f32_e32 v4, v102, v4
	v_mul_f32_e32 v5, v98, v5
	v_mul_f32_e32 v6, v103, v6
	v_mul_f32_e32 v7, v99, v7
	v_cvt_pk_bf16_f32 v96, v0, v2
	v_cvt_pk_bf16_f32 v97, v4, v6
	v_cvt_pk_bf16_f32 v98, v1, v3
	v_cvt_pk_bf16_f32 v99, v5, v7
	s_nop 1
	v_mov_b32_e32 v0, v240
	v_mov_b32_e32 v1, v241
	v_mov_b32_e32 v2, v242
	v_mov_b32_e32 v3, v243
	v_mov_b32_e32 v4, v244
	v_mov_b32_e32 v5, v245
	v_mov_b32_e32 v6, v246
	v_mov_b32_e32 v7, v247
	global_load_dwordx4 v[240:243], v24, s[0:1] offset:272
	global_load_dwordx4 v[244:247], v24, s[0:1] offset:256
	v_mul_f32_e32 v8, v40, v75
	v_add_co_u32_e32 v76, vcc, s88, v28
	v_mul_f32_e32 v4, v4, v8
	v_mul_f32_e32 v8, v40, v82
	v_mul_f32_e32 v0, v0, v8
	v_mul_f32_e32 v8, v40, v74
	v_mul_f32_e32 v5, v5, v8
	v_mul_f32_e32 v8, v40, v80
	v_mul_f32_e32 v1, v1, v8
	v_mul_f32_e32 v8, v40, v79
	v_mul_f32_e32 v6, v6, v8
	v_mul_f32_e32 v8, v40, v86
	v_mul_f32_e32 v2, v2, v8
	v_mul_f32_e32 v8, v40, v78
	v_mul_f32_e32 v7, v7, v8
	v_mul_f32_e32 v8, v40, v85
	v_mul_f32_e32 v3, v3, v8
	v_cvt_pk_bf16_f32 v100, v4, v5
	v_cvt_pk_bf16_f32 v101, v6, v7
	v_cvt_pk_bf16_f32 v102, v0, v1
	v_cvt_pk_bf16_f32 v103, v2, v3
	s_nop 1
	v_mov_b32_e32 v0, v248
	v_mov_b32_e32 v1, v249
	v_mov_b32_e32 v2, v250
	v_mov_b32_e32 v3, v251
	v_mov_b32_e32 v4, v220
	v_mov_b32_e32 v5, v221
	v_mov_b32_e32 v6, v222
	v_mov_b32_e32 v7, v223
	global_load_dwordx4 v[248:251], v24, s[0:1] offset:336
	global_load_dwordx4 v[220:223], v24, s[0:1] offset:320
	v_mul_f32_e32 v8, v40, v84
	v_addc_co_u32_e32 v77, vcc, 0, v29, vcc
	v_mul_f32_e32 v4, v8, v4
	v_mul_f32_e32 v8, v40, v95
	v_mul_f32_e32 v0, v8, v0
	v_mul_f32_e32 v8, v40, v83
	v_mul_f32_e32 v5, v8, v5
	v_mul_f32_e32 v8, v40, v93
	v_mul_f32_e32 v1, v8, v1
	v_mul_f32_e32 v8, v40, v88
	v_mul_f32_e32 v6, v8, v6
	v_mul_f32_e32 v8, v40, v105
	v_mul_f32_e32 v2, v8, v2
	v_mul_f32_e32 v8, v40, v87
	v_mul_f32_e32 v7, v8, v7
	v_mul_f32_e32 v8, v40, v104
	v_mul_f32_e32 v3, v8, v3
	v_cvt_pk_bf16_f32 v104, v4, v5
	v_cvt_pk_bf16_f32 v105, v6, v7
	v_cvt_pk_bf16_f32 v106, v0, v1
	v_cvt_pk_bf16_f32 v107, v2, v3
	s_nop 1
	v_mov_b32_e32 v0, v232
	v_mov_b32_e32 v1, v233
	v_mov_b32_e32 v2, v234
	v_mov_b32_e32 v3, v235
	v_mov_b32_e32 v4, v236
	v_mov_b32_e32 v5, v237
	v_mov_b32_e32 v6, v238
	v_mov_b32_e32 v7, v239
	global_load_dwordx4 v[232:235], v24, s[0:1] offset:400
	global_load_dwordx4 v[236:239], v24, s[0:1] offset:384
	v_mul_f32_e32 v8, v40, v108
	v_mul_f32_e32 v4, v8, v4
	v_mul_f32_e32 v8, v40, v112
	v_mul_f32_e32 v0, v8, v0
	v_mul_f32_e32 v8, v40, v91
	v_mul_f32_e32 v5, v8, v5
	v_mul_f32_e32 v8, v40, v110
	v_mul_f32_e32 v1, v8, v1
	v_mul_f32_e32 v8, v40, v94
	v_mul_f32_e32 v6, v8, v6
	v_mul_f32_e32 v8, v40, v111
	v_mul_f32_e32 v2, v8, v2
	v_mul_f32_e32 v8, v40, v89
	v_mul_f32_e32 v7, v8, v7
	v_mul_f32_e32 v8, v40, v109
	v_mul_f32_e32 v3, v8, v3
	v_cvt_pk_bf16_f32 v108, v4, v5
	v_cvt_pk_bf16_f32 v109, v6, v7
	v_cvt_pk_bf16_f32 v110, v0, v1
	v_cvt_pk_bf16_f32 v111, v2, v3
	s_waitcnt vmcnt(4)
	s_nop 1
	v_mov_b32_e32 v0, v240
	v_mov_b32_e32 v1, v241
	v_mov_b32_e32 v2, v242
	v_mov_b32_e32 v3, v243
	v_mov_b32_e32 v4, v244
	v_mov_b32_e32 v5, v245
	v_mov_b32_e32 v6, v246
	v_mov_b32_e32 v7, v247
	global_load_dwordx4 v[240:243], v24, s[0:1] offset:464
	global_load_dwordx4 v[244:247], v24, s[0:1] offset:448
	v_mul_f32_e32 v8, v40, v113
	v_mul_f32_e32 v4, v8, v4
	v_mul_f32_e32 v8, v40, v131
	v_mul_f32_e32 v0, v8, v0
	v_mul_f32_e32 v8, v40, v114
	v_mul_f32_e32 v5, v8, v5
	v_mul_f32_e32 v8, v40, v132
	v_mul_f32_e32 v1, v8, v1
	v_mul_f32_e32 v8, v40, v115
	v_mul_f32_e32 v6, v8, v6
	v_mul_f32_e32 v8, v40, v133
	v_mul_f32_e32 v2, v8, v2
	v_mul_f32_e32 v8, v40, v130
	v_mul_f32_e32 v7, v8, v7
	v_mul_f32_e32 v8, v40, v134
	v_mul_f32_e32 v3, v8, v3
	v_cvt_pk_bf16_f32 v112, v4, v5
	v_cvt_pk_bf16_f32 v113, v6, v7
	v_cvt_pk_bf16_f32 v114, v0, v1
	v_cvt_pk_bf16_f32 v115, v2, v3
	s_waitcnt vmcnt(4)
	s_nop 1
	v_mov_b32_e32 v0, v248
	v_mov_b32_e32 v1, v249
	v_mov_b32_e32 v2, v250
	v_mov_b32_e32 v3, v251
	v_mov_b32_e32 v4, v220
	v_mov_b32_e32 v5, v221
	v_mov_b32_e32 v6, v222
	v_mov_b32_e32 v7, v223
	v_mul_f32_e32 v8, v40, v128
	v_mul_f32_e32 v4, v8, v4
	v_mul_f32_e32 v8, v40, v129
	v_mul_f32_e32 v0, v8, v0
	v_mul_f32_e32 v8, v40, v126
	v_mul_f32_e32 v5, v8, v5
	v_mul_f32_e32 v8, v40, v127
	v_mul_f32_e32 v1, v8, v1
	v_mul_f32_e32 v8, v40, v118
	v_mul_f32_e32 v6, v8, v6
	v_mul_f32_e32 v8, v40, v119
	v_mul_f32_e32 v2, v8, v2
	v_mul_f32_e32 v8, v40, v116
	v_mul_f32_e32 v7, v8, v7
	v_mul_f32_e32 v8, v40, v117
	v_mul_f32_e32 v3, v8, v3
	v_cvt_pk_bf16_f32 v116, v4, v5
	v_cvt_pk_bf16_f32 v117, v6, v7
	v_cvt_pk_bf16_f32 v118, v0, v1
	v_cvt_pk_bf16_f32 v119, v2, v3
	s_waitcnt vmcnt(2)
	s_nop 1
	v_mov_b32_e32 v0, v232
	v_mov_b32_e32 v1, v233
	v_mov_b32_e32 v2, v234
	v_mov_b32_e32 v3, v235
	v_mov_b32_e32 v4, v236
	v_mov_b32_e32 v5, v237
	v_mov_b32_e32 v6, v238
	v_mov_b32_e32 v7, v239
	v_mul_f32_e32 v8, v40, v124
	v_mul_f32_e32 v4, v8, v4
	v_mul_f32_e32 v8, v40, v125
	v_mul_f32_e32 v8, v8, v0
	v_mul_f32_e32 v0, v40, v122
	v_mul_f32_e32 v0, v0, v5
	v_mul_f32_e32 v5, v40, v123
	v_mul_f32_e32 v5, v5, v1
	v_mul_f32_e32 v1, v40, v120
	v_mul_f32_e32 v1, v1, v6
	v_mul_f32_e32 v6, v40, v121
	v_mul_f32_e32 v6, v6, v2
	v_mul_f32_e32 v2, v40, v90
	v_mul_f32_e32 v2, v2, v7
	v_mul_f32_e32 v7, v40, v92
	v_mul_f32_e32 v3, v7, v3
	v_cvt_pk_bf16_f32 v0, v4, v0
	v_cvt_pk_bf16_f32 v1, v1, v2
	v_cvt_pk_bf16_f32 v2, v8, v5
	v_cvt_pk_bf16_f32 v3, v6, v3
	ds_write_b128 v171, v[0:3]
	s_waitcnt vmcnt(0)
	s_nop 1
	v_mov_b32_e32 v0, v240
	v_mov_b32_e32 v1, v241
	v_mov_b32_e32 v2, v242
	v_mov_b32_e32 v3, v243
	v_mov_b32_e32 v4, v244
	v_mov_b32_e32 v5, v245
	v_mov_b32_e32 v6, v246
	v_mov_b32_e32 v7, v247
	v_mul_f32_e32 v8, v40, v22
	v_mul_f32_e32 v4, v8, v4
	v_mul_f32_e32 v8, v40, v81
	v_mul_f32_e32 v8, v8, v0
	v_mul_f32_e32 v0, v40, v20
	v_mul_f32_e32 v0, v0, v5
	v_mul_f32_e32 v5, v40, v18
	v_mul_f32_e32 v5, v5, v1
	v_mul_f32_e32 v1, v40, v21
	v_mul_f32_e32 v1, v1, v6
	v_mul_f32_e32 v6, v40, v23
	v_mul_f32_e32 v6, v6, v2
	v_mul_f32_e32 v2, v40, v16
	v_mul_f32_e32 v2, v2, v7
	v_mul_f32_e32 v7, v40, v17
	v_mul_f32_e32 v3, v7, v3
	v_cvt_pk_bf16_f32 v0, v4, v0
	v_cvt_pk_bf16_f32 v1, v1, v2
	v_cvt_pk_bf16_f32 v2, v8, v5
	v_cvt_pk_bf16_f32 v3, v6, v3
	ds_write_b128 v171, v[0:3] offset:1024
	global_load_dwordx4 v[4:7], v24, s[0:1] offset:528
	global_load_dwordx4 v[16:19], v24, s[0:1] offset:512
	global_load_dwordx4 v[8:11], v24, s[0:1] offset:592
	global_load_dwordx4 v[20:23], v24, s[0:1] offset:576
	global_load_dwordx4 v[0:3], v[28:29], off offset:16
	global_load_dwordx4 v[12:15], v[28:29], off
	global_load_dwordx4 v[68:71], v[76:77], off
	global_load_dwordx4 v[72:75], v[54:55], off offset:16
	v_pk_mul_f32 v[54:55], v[40:41], v[64:65] op_sel_hi:[0,1]
	s_waitcnt vmcnt(6)
	v_mov_b32_e32 v64, v16
	s_waitcnt vmcnt(4)
	v_mov_b32_e32 v65, v20
	v_pk_mul_f32 v[54:55], v[54:55], v[64:65]
	s_waitcnt vmcnt(2)
	v_mov_b32_e32 v64, v12
	s_waitcnt vmcnt(1)
	v_mov_b32_e32 v65, v68
	v_pk_mul_f32 v[64:65], v[54:55], v[64:65]
	v_mov_b32_e32 v20, v17
	v_sub_f32_e32 v16, v64, v65
	v_mov_b32_e32 v64, v68
	v_mov_b32_e32 v65, v12
	v_pk_mul_f32 v[64:65], v[54:55], v[64:65]
	v_cndmask_b32_e64 v25, v54, v16, s[2:3]
	v_add_f32_e32 v12, v65, v64
	v_cndmask_b32_e64 v64, v55, v12, s[2:3]
	v_pk_mul_f32 v[54:55], v[40:41], v[62:63] op_sel_hi:[0,1]
	v_pk_mul_f32 v[16:17], v[54:55], v[20:21]
	v_mov_b32_e32 v68, v13
	v_pk_mul_f32 v[20:21], v[16:17], v[68:69]
	v_or_b32_e32 v65, 32, v176
	v_sub_f32_e32 v12, v20, v21
	v_cndmask_b32_e64 v20, v16, v12, s[2:3]
	v_mov_b32_e32 v12, v69
	v_pk_mul_f32 v[12:13], v[16:17], v[12:13]
	v_mov_b32_e32 v16, v18
	v_add_f32_e32 v12, v13, v12
	v_cndmask_b32_e64 v21, v17, v12, s[2:3]
	v_pk_mul_f32 v[12:13], v[40:41], v[60:61] op_sel_hi:[0,1]
	v_mov_b32_e32 v17, v22
	v_pk_mul_f32 v[12:13], v[12:13], v[16:17]
	v_mov_b32_e32 v16, v14
	v_mov_b32_e32 v17, v70
	v_pk_mul_f32 v[16:17], v[12:13], v[16:17]
	v_mov_b32_e32 v22, v19
	v_sub_f32_e32 v16, v16, v17
	v_cndmask_b32_e64 v18, v12, v16, s[2:3]
	v_mov_b32_e32 v16, v70
	v_mov_b32_e32 v17, v14
	v_pk_mul_f32 v[16:17], v[12:13], v[16:17]
	v_mov_b32_e32 v70, v15
	v_add_f32_e32 v12, v17, v16
	v_cndmask_b32_e64 v54, v13, v12, s[2:3]
	v_pk_mul_f32 v[12:13], v[40:41], v[58:59] op_sel_hi:[0,1]
	v_pk_mul_f32 v[12:13], v[12:13], v[22:23]
	v_mul_u32_u24_e32 v59, 0x180, v168
	v_pk_mul_f32 v[16:17], v[12:13], v[70:71]
	s_nop 0
	v_sub_f32_e32 v14, v16, v17
	v_cndmask_b32_e64 v16, v12, v14, s[2:3]
	v_mov_b32_e32 v14, v71
	v_pk_mul_f32 v[14:15], v[12:13], v[14:15]
	s_nop 0
	v_add_f32_e32 v12, v15, v14
	v_cndmask_b32_e64 v17, v13, v12, s[2:3]
	v_pk_mul_f32 v[12:13], v[40:41], v[50:51] op_sel_hi:[0,1]
	v_mov_b32_e32 v14, v4
	v_mov_b32_e32 v15, v8
	v_pk_mul_f32 v[12:13], v[12:13], v[14:15]
	v_mov_b32_e32 v14, v0
	s_waitcnt vmcnt(0)
	v_mov_b32_e32 v15, v72
	v_pk_mul_f32 v[14:15], v[12:13], v[14:15]
	v_mov_b32_e32 v8, v5
	v_sub_f32_e32 v4, v14, v15
	v_mov_b32_e32 v14, v72
	v_mov_b32_e32 v15, v0
	v_pk_mul_f32 v[14:15], v[12:13], v[14:15]
	v_cndmask_b32_e64 v19, v12, v4, s[2:3]
	v_add_f32_e32 v0, v15, v14
	v_cndmask_b32_e64 v14, v13, v0, s[2:3]
	v_pk_mul_f32 v[12:13], v[40:41], v[48:49] op_sel_hi:[0,1]
	v_pk_mul_f32 v[4:5], v[12:13], v[8:9]
	v_mov_b32_e32 v72, v1
	v_pk_mul_f32 v[8:9], v[4:5], v[72:73]
	s_nop 0
	v_sub_f32_e32 v0, v8, v9
	v_cndmask_b32_e64 v8, v4, v0, s[2:3]
	v_mov_b32_e32 v0, v73
	v_pk_mul_f32 v[0:1], v[4:5], v[0:1]
	v_mov_b32_e32 v4, v6
	v_add_f32_e32 v0, v1, v0
	v_cndmask_b32_e64 v9, v5, v0, s[2:3]
	v_pk_mul_f32 v[0:1], v[40:41], v[38:39] op_sel_hi:[0,1]
	v_mov_b32_e32 v5, v10
	v_pk_mul_f32 v[0:1], v[0:1], v[4:5]
	v_mov_b32_e32 v4, v2
	v_mov_b32_e32 v5, v74
	v_pk_mul_f32 v[4:5], v[0:1], v[4:5]
	v_mov_b32_e32 v10, v7
	v_sub_f32_e32 v4, v4, v5
	v_cndmask_b32_e64 v6, v0, v4, s[2:3]
	v_mov_b32_e32 v4, v74
	v_mov_b32_e32 v5, v2
	v_pk_mul_f32 v[4:5], v[0:1], v[4:5]
	v_mov_b32_e32 v74, v3
	v_add_f32_e32 v0, v5, v4
	v_cndmask_b32_e64 v12, v1, v0, s[2:3]
	v_pk_mul_f32 v[0:1], v[40:41], v[36:37] op_sel_hi:[0,1]
	v_pk_mul_f32 v[0:1], v[0:1], v[10:11]
	s_nop 0
	v_pk_mul_f32 v[4:5], v[0:1], v[74:75]
	s_nop 0
	v_sub_f32_e32 v2, v4, v5
	v_cndmask_b32_e64 v4, v0, v2, s[2:3]
	v_mov_b32_e32 v2, v75
	v_pk_mul_f32 v[2:3], v[0:1], v[2:3]
	s_nop 0
	v_add_f32_e32 v0, v3, v2
	v_cndmask_b32_e64 v5, v1, v0, s[2:3]
	v_cvt_pk_bf16_f32 v0, v25, v20
	v_cvt_pk_bf16_f32 v1, v18, v16
	v_cvt_pk_bf16_f32 v2, v19, v8
	v_cvt_pk_bf16_f32 v3, v6, v4
	ds_write_b128 v171, v[0:3] offset:2048
	v_cvt_pk_bf16_f32 v0, v64, v21
	v_cvt_pk_bf16_f32 v1, v54, v17
	v_cvt_pk_bf16_f32 v2, v14, v9
	v_cvt_pk_bf16_f32 v3, v12, v5
	ds_write_b128 v171, v[0:3] offset:3072
	global_load_dwordx4 v[0:3], v24, s[0:1] offset:656
	global_load_dwordx4 v[4:7], v24, s[0:1] offset:640
	global_load_dwordx4 v[8:11], v24, s[0:1] offset:720
	global_load_dwordx4 v[12:15], v24, s[0:1] offset:704
	global_load_dwordx4 v[16:19], v[28:29], off offset:80
	global_load_dwordx4 v[20:23], v[28:29], off offset:64
	global_load_dwordx4 v[36:39], v[76:77], off offset:64
	global_load_dwordx4 v[48:51], v[44:45], off offset:16
	v_pk_mul_f32 v[24:25], v[40:41], v[56:57] op_sel_hi:[0,1]
	s_waitcnt vmcnt(6)
	v_mov_b32_e32 v28, v4
	s_waitcnt vmcnt(4)
	v_mov_b32_e32 v29, v12
	v_pk_mul_f32 v[24:25], v[24:25], v[28:29]
	s_waitcnt vmcnt(2)
	v_mov_b32_e32 v28, v20
	s_waitcnt vmcnt(1)
	v_mov_b32_e32 v29, v36
	v_pk_mul_f32 v[28:29], v[24:25], v[28:29]
	v_mov_b32_e32 v12, v5
	v_sub_f32_e32 v4, v28, v29
	v_mov_b32_e32 v28, v36
	v_mov_b32_e32 v29, v20
	v_pk_mul_f32 v[28:29], v[24:25], v[28:29]
	v_cndmask_b32_e64 v44, v24, v4, s[2:3]
	v_add_f32_e32 v4, v29, v28
	v_cndmask_b32_e64 v28, v25, v4, s[2:3]
	v_pk_mul_f32 v[24:25], v[40:41], v[52:53] op_sel_hi:[0,1]
	v_pk_mul_f32 v[4:5], v[24:25], v[12:13]
	v_mov_b32_e32 v36, v21
	v_pk_mul_f32 v[12:13], v[4:5], v[36:37]
	v_mov_b32_e32 v20, v37
	v_sub_f32_e32 v12, v12, v13
	v_cndmask_b32_e64 v24, v4, v12, s[2:3]
	v_pk_mul_f32 v[12:13], v[4:5], v[20:21]
	s_nop 0
	v_add_f32_e32 v4, v13, v12
	v_cndmask_b32_e64 v20, v5, v4, s[2:3]
	v_pk_mul_f32 v[4:5], v[40:41], v[46:47] op_sel_hi:[0,1]
	v_mov_b32_e32 v12, v6
	v_mov_b32_e32 v13, v14
	v_pk_mul_f32 v[4:5], v[4:5], v[12:13]
	v_mov_b32_e32 v12, v22
	v_mov_b32_e32 v13, v38
	v_pk_mul_f32 v[12:13], v[4:5], v[12:13]
	v_mov_b32_e32 v14, v7
	v_sub_f32_e32 v6, v12, v13
	v_mov_b32_e32 v12, v38
	v_mov_b32_e32 v13, v22
	v_pk_mul_f32 v[12:13], v[4:5], v[12:13]
	v_cndmask_b32_e64 v21, v4, v6, s[2:3]
	v_add_f32_e32 v4, v13, v12
	v_cndmask_b32_e64 v12, v5, v4, s[2:3]
	v_pk_mul_f32 v[4:5], v[40:41], v[42:43] op_sel_hi:[0,1]
	v_pk_mul_f32 v[4:5], v[4:5], v[14:15]
	v_mov_b32_e32 v38, v23
	v_pk_mul_f32 v[6:7], v[4:5], v[38:39]
	v_mov_b32_e32 v22, v39
	v_sub_f32_e32 v6, v6, v7
	v_cndmask_b32_e64 v13, v4, v6, s[2:3]
	v_pk_mul_f32 v[6:7], v[4:5], v[22:23]
	s_nop 0
	v_add_f32_e32 v4, v7, v6
	v_cndmask_b32_e64 v14, v5, v4, s[2:3]
	v_pk_mul_f32 v[4:5], v[40:41], v[34:35] op_sel_hi:[0,1]
	v_mov_b32_e32 v6, v0
	v_mov_b32_e32 v7, v8
	v_pk_mul_f32 v[4:5], v[4:5], v[6:7]
	v_mov_b32_e32 v6, v16
	s_waitcnt vmcnt(0)
	v_mov_b32_e32 v7, v48
	v_pk_mul_f32 v[6:7], v[4:5], v[6:7]
	v_mov_b32_e32 v8, v1
	v_sub_f32_e32 v0, v6, v7
	v_mov_b32_e32 v6, v48
	v_mov_b32_e32 v7, v16
	v_pk_mul_f32 v[6:7], v[4:5], v[6:7]
	v_cndmask_b32_e64 v15, v4, v0, s[2:3]
	v_add_f32_e32 v0, v7, v6
	v_cndmask_b32_e64 v6, v5, v0, s[2:3]
	v_pk_mul_f32 v[4:5], v[40:41], v[32:33] op_sel_hi:[0,1]
	v_pk_mul_f32 v[0:1], v[4:5], v[8:9]
	v_mov_b32_e32 v48, v17
	v_pk_mul_f32 v[4:5], v[0:1], v[48:49]
	v_mov_b32_e32 v16, v49
	v_sub_f32_e32 v4, v4, v5
	v_cndmask_b32_e64 v7, v0, v4, s[2:3]
	v_pk_mul_f32 v[4:5], v[0:1], v[16:17]
	v_mov_b32_e32 v49, v177
	v_add_f32_e32 v0, v5, v4
	v_cndmask_b32_e64 v8, v1, v0, s[2:3]
	v_pk_mul_f32 v[0:1], v[40:41], v[30:31] op_sel_hi:[0,1]
	v_mov_b32_e32 v4, v2
	v_mov_b32_e32 v5, v10
	v_pk_mul_f32 v[0:1], v[0:1], v[4:5]
	v_mov_b32_e32 v4, v18
	v_mov_b32_e32 v5, v50
	v_pk_mul_f32 v[4:5], v[0:1], v[4:5]
	v_mov_b32_e32 v10, v3
	v_sub_f32_e32 v2, v4, v5
	v_mov_b32_e32 v4, v50
	v_mov_b32_e32 v5, v18
	v_pk_mul_f32 v[4:5], v[0:1], v[4:5]
	v_cndmask_b32_e64 v9, v0, v2, s[2:3]
	v_add_f32_e32 v0, v5, v4
	v_cndmask_b32_e64 v4, v1, v0, s[2:3]
	v_pk_mul_f32 v[0:1], v[40:41], v[26:27] op_sel_hi:[0,1]
	v_pk_mul_f32 v[0:1], v[0:1], v[10:11]
	v_mov_b32_e32 v50, v19
	v_pk_mul_f32 v[2:3], v[0:1], v[50:51]
	v_mov_b32_e32 v18, v51
	v_sub_f32_e32 v2, v2, v3
	v_cndmask_b32_e64 v5, v0, v2, s[2:3]
	v_pk_mul_f32 v[2:3], v[0:1], v[18:19]
	v_lshlrev_b32_e32 v18, 4, v41
	v_add_f32_e32 v0, v3, v2
	v_cndmask_b32_e64 v10, v1, v0, s[2:3]
	v_cvt_pk_bf16_f32 v0, v44, v24
	v_cvt_pk_bf16_f32 v1, v21, v13
	v_cvt_pk_bf16_f32 v2, v15, v7
	v_cvt_pk_bf16_f32 v3, v9, v5
	ds_write_b128 v171, v[0:3] offset:4096
	v_cvt_pk_bf16_f32 v0, v28, v20
	v_cvt_pk_bf16_f32 v1, v12, v14
	v_cvt_pk_bf16_f32 v2, v6, v8
	v_cvt_pk_bf16_f32 v3, v4, v10
	ds_write_b128 v171, v[0:3] offset:5120
	v_and_b32_e32 v1, 0xfffff0, v148
	v_lshlrev_b32_e32 v3, 1, v148
	v_lshlrev_b32_e32 v0, 3, v41
	v_and_or_b32 v1, v3, 8, v1
	v_and_b32_e32 v2, 0x78, v0
	v_lshrrev_b32_e32 v3, 1, v148
	v_lshrrev_b32_e32 v1, 1, v1
	v_bfe_u32 v0, v0, 5, 2
	v_and_b32_e32 v4, 3, v148
	v_or_b32_e32 v1, v1, v0
	v_and_or_b32 v3, v3, 4, v4
	v_lshlrev_b32_e32 v1, 9, v1
	v_lshlrev_b32_e32 v3, 6, v3
	v_and_b32_e32 v4, 48, v18
	v_or3_b32 v19, v1, v3, v4
	v_add_u32_e32 v1, 32, v148
	v_and_b32_e32 v5, 0xfffff0, v1
	v_lshlrev_b32_e32 v1, 1, v1
	v_and_or_b32 v1, v1, 8, v5
	v_lshrrev_b32_e32 v1, 1, v1
	v_or_b32_e32 v0, v1, v0
	v_lshlrev_b32_e32 v0, 9, v0
	s_mov_b32 s2, 0x2aaaaaab
	v_or3_b32 v20, v0, v3, v4
	v_mul_hi_i32 v0, v41, s2
	v_lshrrev_b32_e32 v1, 31, v0
	v_ashrrev_i32_e32 v0, 2, v0
	v_add_u32_e32 v150, v0, v1
	v_add_u32_e32 v1, 0x200, v41
	v_mul_hi_i32 v3, v1, s2
	v_lshrrev_b32_e32 v4, 31, v3
	v_ashrrev_i32_e32 v3, 2, v3
	v_add_u32_e32 v152, v3, v4
	v_mul_lo_u32 v3, v152, 24
	v_sub_u32_e32 v1, v1, v3
	v_add_u32_e32 v3, 0x400, v41
	v_mul_hi_i32 v4, v3, s2
	v_lshrrev_b32_e32 v5, 31, v4
	v_ashrrev_i32_e32 v4, 2, v4
	v_mul_lo_u32 v0, v150, 24
	v_add_u32_e32 v154, v4, v5
	s_add_u32 s2, s94, s44
	v_sub_u32_e32 v0, v41, v0
	v_mul_lo_u32 v4, v154, 24
	s_addc_u32 s3, s95, 0
	s_lshl_b32 s5, s5, 8
	v_lshlrev_b32_e32 v8, 3, v0
	v_sub_u32_e32 v3, v3, v4
	v_mul_lo_u32 v4, v150, s89
	v_bitop3_b32 v0, v150, v0, 7 bitop3:0x6c
	s_add_u32 s6, s38, s5
	v_lshlrev_b32_e32 v12, 3, v1
	v_lshl_add_u32 v21, v0, 4, v4
	v_mul_lo_u32 v0, v152, s89
	v_bitop3_b32 v1, v152, v1, 7 bitop3:0x6c
	s_addc_u32 s7, s39, 0
	s_ashr_i32 s5, s4, 31
	v_ashrrev_i32_e32 v151, 31, v150
	v_lshl_add_u32 v22, v1, 4, v0
	v_mul_lo_u32 v0, v154, s89
	v_bitop3_b32 v1, v154, v3, 7 bitop3:0x6c
	v_lshl_add_u64 v[10:11], v[150:151], 0, s[4:5]
	v_mov_b64_e32 v[52:53], s[2:3]
	v_lshlrev_b32_e32 v16, 3, v3
	v_lshl_add_u32 v23, v1, 4, v0
	v_lshlrev_b32_e32 v0, 3, v66
	v_and_b32_e32 v1, 0xc0, v67
	v_lshlrev_b32_e32 v3, 1, v41
	v_ashrrev_i32_e32 v9, 31, v8
	v_mad_u64_u32 v[14:15], s[18:19], v10, s87, v[52:53]
	v_and_or_b32 v1, v0, 24, v1
	v_and_b32_e32 v3, 32, v3
	v_and_b32_e32 v0, 0x100, v0
	v_mad_i32_i24 v15, v11, s87, v15
	v_lshlrev_b64 v[50:51], 1, v[8:9]
	v_ashrrev_i32_e32 v153, 31, v152
	v_or3_b32 v58, v1, v3, v0
	v_lshl_add_u64 v[0:1], v[148:149], 0, s[4:5]
	v_lshl_add_u64 v[8:9], v[14:15], 0, v[50:51]
	v_lshl_add_u64 v[14:15], v[152:153], 0, s[4:5]
	v_lshlrev_b64 v[0:1], 11, v[0:1]
	v_ashrrev_i32_e32 v13, 31, v12
	v_mad_u64_u32 v[24:25], s[18:19], v14, s87, v[52:53]
	v_lshl_add_u64 v[0:1], s[6:7], 0, v[0:1]
	v_lshlrev_b32_e32 v48, 1, v2
	v_mad_i32_i24 v25, v15, s87, v25
	v_lshlrev_b64 v[54:55], 1, v[12:13]
	v_ashrrev_i32_e32 v155, 31, v154
	v_lshl_add_u64 v[0:1], v[0:1], 0, v[48:49]
	v_lshl_add_u64 v[4:5], v[156:157], 0, s[4:5]
	v_lshl_add_u64 v[12:13], v[24:25], 0, v[54:55]
	v_lshl_add_u64 v[24:25], v[154:155], 0, s[4:5]
	global_load_dwordx4 v[0:3], v[0:1], off
	v_lshlrev_b64 v[4:5], 11, v[4:5]
	v_ashrrev_i32_e32 v17, 31, v16
	v_mad_u64_u32 v[26:27], s[18:19], v24, s87, v[52:53]
	v_lshl_add_u64 v[4:5], s[6:7], 0, v[4:5]
	v_mad_i32_i24 v27, v25, s87, v27
	v_lshlrev_b64 v[56:57], 1, v[16:17]
	v_lshl_add_u64 v[4:5], v[4:5], 0, v[48:49]
	v_lshl_add_u64 v[16:17], v[26:27], 0, v[56:57]
	global_load_dwordx4 v[4:7], v[4:5], off
	v_add_u32_e32 v182, 0, v19
	global_load_dwordx4 v[8:11], v[8:9], off
	v_and_b32_e32 v72, 0x70, v18
	global_load_dwordx4 v[12:15], v[12:13], off
	v_add_u32_e32 v183, 0, v20
	global_load_dwordx4 v[24:27], v[16:17], off
	s_waitcnt vmcnt(0)
	v_add_u32_e32 v184, 0, v21
	v_add_u32_e32 v185, 0, v22
	v_add_u32_e32 v186, 0, v23
	v_bitop3_b32 v60, v65, v59, v72 bitop3:0xde
	v_add_u32_e32 v189, 0, v60
	s_movk_i32 s5, 0x80
	s_mov_b32 s44, s45
	v_add_u32_e32 v172, s16, v58
	v_lshl_add_u64 v[160:161], s[6:7], 0, v[48:49]
	v_lshl_add_u64 v[162:163], s[2:3], 0, v[50:51]
	v_lshl_add_u64 v[164:165], s[2:3], 0, v[54:55]
	v_lshl_add_u64 v[166:167], s[2:3], 0, v[56:57]
	v_cmp_gt_u32_e64 s[2:3], 32, v66
	s_waitcnt vmcnt(4)
	ds_write_b128 v182, v[0:3]
	v_mov_b32_e32 v0, 0x3000
	v_mad_u32_u24 v71, v168, s89, v0
	v_bitop3_b32 v0, v176, v59, v72 bitop3:0xde
	v_add_u32_e32 v187, 0, v0
	v_bitop3_b32 v67, v65, v71, v72 bitop3:0xde
	v_bitop3_b32 v64, v176, v71, v72 bitop3:0xde
	v_add_u32_e32 v202, 0, v64
	v_add_u32_e32 v201, 0, v67
	s_waitcnt vmcnt(3)
	ds_write_b128 v183, v[4:7]
	s_waitcnt vmcnt(2)
	ds_write_b128 v184, v[8:11] offset:32768
	s_waitcnt vmcnt(1)
	ds_write_b128 v185, v[12:15] offset:32768
	v_mov_b64_e32 v[0:1], s[44:45]
	s_waitcnt vmcnt(0)
	ds_write_b128 v186, v[24:27] offset:32768
	s_waitcnt lgkmcnt(0)
	s_barrier
	ds_read_b128 v[16:19], v187 offset:32768
	ds_read_b128 v[20:23], v187 offset:45056
	ds_read_b128 v[60:63], v189 offset:32768
	ds_read_b128 v[74:77], v189 offset:45056
	s_waitcnt lgkmcnt(3)
	v_mfma_f32_32x32x16_bf16 v[32:47], v[16:19], v[96:99], 0
	v_mov_b64_e32 v[14:15], s[58:59]
	v_mov_b64_e32 v[2:3], s[46:47]
	v_mov_b64_e32 v[4:5], s[48:49]
	v_mov_b64_e32 v[6:7], s[50:51]
	v_mov_b64_e32 v[8:9], s[52:53]
	v_mov_b64_e32 v[10:11], s[54:55]
	v_mov_b64_e32 v[12:13], s[56:57]
	s_waitcnt lgkmcnt(2)
	v_mfma_f32_32x32x16_bf16 v[16:31], v[20:23], v[96:99], 0
	s_waitcnt lgkmcnt(1)
	v_mfma_f32_32x32x16_bf16 v[32:47], v[60:63], v[100:103], v[32:47]
	v_or_b32_e32 v60, 64, v176
	v_bitop3_b32 v61, v60, v59, v72 bitop3:0xde
	v_add_u32_e32 v190, 0, v61
	ds_read_b128 v[78:81], v190 offset:45056
	v_bitop3_b32 v61, v60, v71, v72 bitop3:0xde
	v_or_b32_e32 v60, 0x60, v176
	v_bitop3_b32 v59, v60, v59, v72 bitop3:0xde
	s_waitcnt lgkmcnt(1)
	v_mfma_f32_32x32x16_bf16 v[16:31], v[74:77], v[100:103], v[16:31]
	ds_read_b128 v[74:77], v190 offset:32768
	v_add_u32_e32 v191, 0, v59
	v_bitop3_b32 v59, v60, v71, v72 bitop3:0xde
	v_bitop3_b32 v60, v176, v72, s5 bitop3:0x36
	v_mad_u32_u24 v62, v168, s89, v60
	v_add_u32_e32 v192, 0, v62
	s_movk_i32 s5, 0xa0
	s_waitcnt lgkmcnt(0)
	v_mfma_f32_32x32x16_bf16 v[32:47], v[74:77], v[104:107], v[32:47]
	ds_read_b128 v[74:77], v191 offset:32768
	v_bitop3_b32 v62, v176, v72, s5 bitop3:0x36
	v_mad_u32_u24 v63, v168, s89, v62
	v_add_u32_e32 v193, 0, v63
	s_movk_i32 s5, 0xc0
	v_bitop3_b32 v63, v176, v72, s5 bitop3:0x36
	v_mad_u32_u24 v65, v168, s89, v63
	v_mfma_f32_32x32x16_bf16 v[16:31], v[78:81], v[104:107], v[16:31]
	ds_read_b128 v[78:81], v191 offset:45056
	v_add_u32_e32 v194, 0, v65
	s_movk_i32 s5, 0xe0
	v_bitop3_b32 v65, v176, v72, s5 bitop3:0x36
	v_mad_u32_u24 v68, v168, s89, v65
	v_add_u32_e32 v195, 0, v68
	s_movk_i32 s5, 0x100
	s_waitcnt lgkmcnt(1)
	v_mfma_f32_32x32x16_bf16 v[32:47], v[74:77], v[108:111], v[32:47]
	ds_read_b128 v[74:77], v192 offset:32768
	v_bitop3_b32 v68, v176, v72, s5 bitop3:0x36
	v_mad_u32_u24 v69, v168, s89, v68
	v_add_u32_e32 v196, 0, v69
	s_movk_i32 s5, 0x120
	v_bitop3_b32 v69, v176, v72, s5 bitop3:0x36
	v_mad_u32_u24 v70, v168, s89, v69
	s_waitcnt lgkmcnt(1)
	v_mfma_f32_32x32x16_bf16 v[16:31], v[78:81], v[108:111], v[16:31]
	ds_read_b128 v[78:81], v192 offset:45056
	v_add_u32_e32 v197, 0, v70
	s_movk_i32 s5, 0x140
	v_bitop3_b32 v70, v176, v72, s5 bitop3:0x36
	v_mad_u32_u24 v73, v168, s89, v70
	v_add_u32_e32 v199, 0, v73
	s_movk_i32 s5, 0x160
	s_waitcnt lgkmcnt(1)
	v_mfma_f32_32x32x16_bf16 v[32:47], v[74:77], v[112:115], v[32:47]
	ds_read_b128 v[74:77], v193 offset:32768
	v_add_u32_e32 v60, v60, v71
	v_add_u32_e32 v62, v62, v71
	v_add_u32_e32 v63, v63, v71
	v_add_u32_e32 v65, v65, v71
	v_add_u32_e32 v68, v68, v71
	v_add_u32_e32 v69, v69, v71
	s_waitcnt lgkmcnt(1)
	v_mfma_f32_32x32x16_bf16 v[16:31], v[78:81], v[112:115], v[16:31]
	ds_read_b128 v[78:81], v193 offset:45056
	v_add_u32_e32 v70, v70, v71
	v_add_u32_e32 v209, 0, v61
	v_add_u32_e32 v212, 0, v59
	v_add_u32_e32 v211, 0, v60
	v_add_u32_e32 v210, 0, v62
	v_add_u32_e32 v208, 0, v63
	s_waitcnt lgkmcnt(1)
	v_mfma_f32_32x32x16_bf16 v[32:47], v[74:77], v[116:119], v[32:47]
	ds_read_b128 v[74:77], v194 offset:32768
	v_add_u32_e32 v207, 0, v65
	v_add_u32_e32 v206, 0, v68
	v_add_u32_e32 v205, 0, v69
	v_add_u32_e32 v204, 0, v70
	s_waitcnt lgkmcnt(1)
	v_mfma_f32_32x32x16_bf16 v[16:31], v[78:81], v[116:119], v[16:31]
	ds_read_b128 v[78:81], v194 offset:45056
	ds_read_b128 v[82:85], v171
	s_waitcnt lgkmcnt(0)
	v_mfma_f32_32x32x16_bf16 v[32:47], v[74:77], v[82:85], v[32:47]
	ds_read_b128 v[74:77], v195 offset:32768
	v_mfma_f32_32x32x16_bf16 v[16:31], v[78:81], v[82:85], v[16:31]
	ds_read_b128 v[78:81], v195 offset:45056
	ds_read_b128 v[82:85], v171 offset:1024
	s_waitcnt lgkmcnt(0)
	v_mfma_f32_32x32x16_bf16 v[32:47], v[74:77], v[82:85], v[32:47]
	ds_read_b128 v[74:77], v196 offset:32768
	v_mfma_f32_32x32x16_bf16 v[16:31], v[78:81], v[82:85], v[16:31]
	ds_read_b128 v[78:81], v196 offset:45056
	ds_read_b128 v[82:85], v171 offset:2048
	s_waitcnt lgkmcnt(0)
	v_mfma_f32_32x32x16_bf16 v[32:47], v[74:77], v[82:85], v[32:47]
	ds_read_b128 v[74:77], v197 offset:32768
	v_mfma_f32_32x32x16_bf16 v[16:31], v[78:81], v[82:85], v[16:31]
	ds_read_b128 v[78:81], v197 offset:45056
	ds_read_b128 v[82:85], v171 offset:3072
	s_waitcnt lgkmcnt(0)
	v_mfma_f32_32x32x16_bf16 v[32:47], v[74:77], v[82:85], v[32:47]
	ds_read_b128 v[74:77], v199 offset:32768
	v_mfma_f32_32x32x16_bf16 v[16:31], v[78:81], v[82:85], v[16:31]
	ds_read_b128 v[78:81], v199 offset:45056
	ds_read_b128 v[82:85], v171 offset:4096
	s_waitcnt lgkmcnt(0)
	v_mfma_f32_32x32x16_bf16 v[32:47], v[74:77], v[82:85], v[32:47]
	v_bitop3_b32 v76, v176, v72, s5 bitop3:0x36
	v_mad_u32_u24 v72, v168, s89, v76
	v_add_u32_e32 v198, 0, v72
	ds_read_b128 v[72:75], v198 offset:32768
	v_add_u32_e32 v71, v76, v71
	v_add_u32_e32 v203, 0, v71
	v_mfma_f32_32x32x16_bf16 v[16:31], v[78:81], v[82:85], v[16:31]
	ds_read_b128 v[76:79], v198 offset:45056
	ds_read_b128 v[80:83], v171 offset:5120
	s_waitcnt lgkmcnt(0)
	v_mfma_f32_32x32x16_bf16 v[32:47], v[72:75], v[80:83], v[32:47]
	v_mov_b32_e32 v74, 0xf149f2ca
	v_mfma_f32_32x32x16_bf16 v[16:31], v[76:79], v[80:83], v[16:31]
	s_nop 9
	v_max_f32_e32 v72, v33, v33
	v_max_f32_e32 v73, v32, v32
	v_max_f32_e32 v72, v73, v72
	v_max3_f32 v72, v72, v34, v35
	v_max3_f32 v72, v72, v36, v37
	v_max3_f32 v72, v72, v38, v39
	v_max3_f32 v72, v72, v40, v41
	v_max3_f32 v72, v72, v42, v43
	v_max3_f32 v72, v72, v44, v45
	v_max3_f32 v72, v72, v46, v47
	v_max3_f32 v72, v72, v16, v17
	v_max3_f32 v72, v72, v18, v19
	v_max3_f32 v72, v72, v20, v21
	v_max3_f32 v72, v72, v22, v23
	v_max3_f32 v72, v72, v24, v25
	v_max3_f32 v72, v72, v26, v27
	v_max3_f32 v72, v72, v28, v29
	v_max3_f32 v72, v72, v30, v31
	v_mov_b32_e32 v73, v72
	s_nop 1
	v_permlane32_swap_b32_e32 v72, v73
	v_max_f32_e32 v73, v73, v73
	v_max_f32_e32 v72, v72, v72
	v_max_f32_e32 v72, v72, v73
	v_add_f32_e32 v73, 0x7149f2ca, v72
	v_cmp_ge_f32_e32 vcc, s90, v73
	s_cmp_eq_u64 vcc, exec
	s_cselect_b64 vcc, -1, 0
	v_max_f32_e32 v72, 0xf149f2ca, v72
	s_add_i32 s18, s15, 0x8040
	v_cndmask_b32_e32 v158, v72, v74, vcc
	s_ashr_i32 s19, s18, 31
	v_sub_f32_e32 v132, v16, v158
	v_sub_f32_e32 v133, v17, v158
	v_lshl_add_u64 v[16:17], v[148:149], 0, s[18:19]
	v_sub_f32_e32 v124, v20, v158
	v_sub_f32_e32 v125, v21, v158
	v_lshlrev_b64 v[16:17], 11, v[16:17]
	v_lshl_add_u64 v[20:21], v[156:157], 0, s[18:19]
	v_sub_f32_e32 v128, v24, v158
	v_sub_f32_e32 v129, v25, v158
	v_lshl_add_u64 v[16:17], s[6:7], 0, v[16:17]
	v_lshlrev_b64 v[20:21], 11, v[20:21]
	v_lshl_add_u64 v[24:25], v[150:151], 0, s[18:19]
	v_sub_f32_e32 v32, v32, v158
	v_sub_f32_e32 v33, v33, v158
	v_sub_f32_e32 v130, v26, v158
	v_sub_f32_e32 v131, v27, v158
	v_sub_f32_e32 v120, v28, v158
	v_sub_f32_e32 v121, v29, v158
	v_lshl_add_u64 v[16:17], v[16:17], 0, v[48:49]
	v_lshl_add_u64 v[20:21], s[6:7], 0, v[20:21]
	v_mad_u64_u32 v[26:27], s[20:21], v24, s87, v[52:53]
	v_lshl_add_u64 v[28:29], v[152:153], 0, s[18:19]
	v_sub_f32_e32 v34, v34, v158
	v_sub_f32_e32 v35, v35, v158
	v_sub_f32_e32 v134, v18, v158
	v_sub_f32_e32 v135, v19, v158
	v_sub_f32_e32 v122, v30, v158
	v_sub_f32_e32 v123, v31, v158
	v_exp_f32_e32 v136, v32
	v_exp_f32_e32 v230, v33
	global_load_dwordx4 v[16:19], v[16:17], off
	v_lshl_add_u64 v[20:21], v[20:21], 0, v[48:49]
	v_mad_i32_i24 v27, v25, s87, v27
	v_mad_u64_u32 v[30:31], s[20:21], v28, s87, v[52:53]
	v_lshl_add_u64 v[32:33], v[154:155], 0, s[18:19]
	v_sub_f32_e32 v126, v22, v158
	v_sub_f32_e32 v127, v23, v158
	v_exp_f32_e32 v137, v34
	v_exp_f32_e32 v229, v35
	global_load_dwordx4 v[20:23], v[20:21], off
	v_lshl_add_u64 v[24:25], v[26:27], 0, v[50:51]
	v_mad_i32_i24 v31, v29, s87, v31
	v_mad_u64_u32 v[34:35], s[18:19], v32, s87, v[52:53]
	global_load_dwordx4 v[24:27], v[24:25], off
	v_lshl_add_u64 v[28:29], v[30:31], 0, v[54:55]
	v_mad_i32_i24 v35, v33, s87, v35
	global_load_dwordx4 v[28:31], v[28:29], off
	v_lshl_add_u64 v[32:33], v[34:35], 0, v[56:57]
	global_load_dwordx4 v[32:35], v[32:33], off
	v_sub_f32_e32 v73, 0xf149f2ca, v72
	v_exp_f32_e32 v73, v73
	v_sub_f32_e32 v36, v36, v158
	v_sub_f32_e32 v37, v37, v158
	v_sub_f32_e32 v38, v38, v158
	v_sub_f32_e32 v39, v39, v158
	v_sub_f32_e32 v40, v40, v158
	v_sub_f32_e32 v41, v41, v158
	v_sub_f32_e32 v42, v42, v158
	v_sub_f32_e32 v43, v43, v158
	v_sub_f32_e32 v44, v44, v158
	v_sub_f32_e32 v45, v45, v158
	v_sub_f32_e32 v46, v46, v158
	v_sub_f32_e32 v47, v47, v158
	v_exp_f32_e32 v138, v36
	v_exp_f32_e32 v228, v37
	v_exp_f32_e32 v139, v38
	v_exp_f32_e32 v213, v39
	v_exp_f32_e32 v144, v40
	v_exp_f32_e32 v147, v41
	v_exp_f32_e32 v145, v42
	v_exp_f32_e32 v146, v43
	v_exp_f32_e32 v141, v44
	v_exp_f32_e32 v143, v45
	v_exp_f32_e32 v140, v46
	v_exp_f32_e32 v142, v47
	s_waitcnt vmcnt(0)
	s_addk_i32 s16, 0x4000
	s_waitcnt vmcnt(4)
	ds_write_b128 v182, v[16:19] offset:16384
	s_waitcnt vmcnt(3)
	ds_write_b128 v183, v[20:23] offset:16384
	s_waitcnt vmcnt(2)
	ds_write_b128 v184, v[24:27] offset:57344
	s_waitcnt vmcnt(1)
	ds_write_b128 v185, v[28:31] offset:57344
	s_waitcnt vmcnt(0)
	ds_write_b128 v186, v[32:35] offset:57344
	v_add_u32_e32 v175, s16, v58
	v_mov_b64_e32 v[46:47], v[14:15]
	v_mov_b64_e32 v[30:31], v[14:15]
	v_mov_b64_e32 v[62:63], v[14:15]
	v_cndmask_b32_e64 v200, v73, 1.0, vcc
	s_add_i32 s15, s4, 0x80
	s_sub_i32 s14, s14, 64
	v_mov_b64_e32 v[44:45], v[12:13]
	v_mov_b64_e32 v[42:43], v[10:11]
	v_mov_b64_e32 v[40:41], v[8:9]
	v_mov_b64_e32 v[38:39], v[6:7]
	v_mov_b64_e32 v[36:37], v[4:5]
	v_mov_b64_e32 v[34:35], v[2:3]
	v_mov_b64_e32 v[32:33], v[0:1]
	v_mov_b64_e32 v[28:29], v[12:13]
	v_mov_b64_e32 v[26:27], v[10:11]
	v_mov_b64_e32 v[24:25], v[8:9]
	v_mov_b64_e32 v[22:23], v[6:7]
	v_mov_b64_e32 v[20:21], v[4:5]
	v_mov_b64_e32 v[18:19], v[2:3]
	v_mov_b64_e32 v[16:17], v[0:1]
	v_mov_b64_e32 v[60:61], v[12:13]
	v_mov_b64_e32 v[58:59], v[10:11]
	v_mov_b64_e32 v[56:57], v[8:9]
	v_mov_b64_e32 v[54:55], v[6:7]
	v_mov_b64_e32 v[52:53], v[4:5]
	v_mov_b64_e32 v[50:51], v[2:3]
	v_mov_b64_e32 v[48:49], v[0:1]
	s_waitcnt lgkmcnt(0)
	s_barrier
